# v050 + residual GEMMs (w_out, w_down) run 4 row tiles x 8 column tiles per XCD round instead of 8x4: activation rows fetched from beyond L2 once instead of twice
# speedup vs baseline: 1.0113x; 1.0038x over previous
.LBB0_258:
	s_or_b64 exec, exec, s[0:1]
	s_cmpk_lt_i32 s75, 0x900
	s_cselect_b64 s[0:1], -1, 0
	v_writelane_b32 v254, s0, 45
	s_mov_b32 s72, 0x3f803f80
	s_mov_b32 s65, 0x1c000
	v_writelane_b32 v254, s1, 46
	s_ashr_i32 s0, s75, 31
	v_writelane_b32 v254, s0, 47
	s_lshr_b32 s0, s0, 29
	s_add_i32 s0, s75, s0
	s_ashr_i32 s1, s0, 3
	s_and_b32 s0, s0, -8
	s_sub_i32 s3, s75, s0
	s_ashr_i32 s0, s84, 31
	v_writelane_b32 v254, s0, 48
	v_mov_b32_e32 v1, 0
	v_readlane_b32 s9, v254, 6
	s_mul_hi_i32 s0, s9, 0x55555556
	s_lshr_b32 s2, s0, 31
	s_add_i32 s0, s0, s2
	s_mul_i32 s0, s0, 3
	s_sub_i32 s59, s9, s0
	s_cmpk_lt_i32 s9, 0x100
	s_cselect_b64 s[4:5], -1, 0
	v_writelane_b32 v254, s4, 49
	s_cmpk_lt_i32 s75, 0x400
	s_mul_i32 s2, s3, 0x81
	v_writelane_b32 v254, s5, 50
	s_cselect_b64 s[4:5], -1, 0
	s_lshl_b32 s0, s3, 7
	v_writelane_b32 v254, s4, 51
	s_cmpk_lt_i32 s75, 0x1600
	s_mov_b32 s89, 0
	v_writelane_b32 v254, s5, 52
	s_cselect_b64 s[4:5], -1, 0
	v_writelane_b32 v254, s4, 53
	s_cmp_lt_i32 s3, 0
	s_cselect_b32 s2, s2, s0
	v_writelane_b32 v254, s5, 54
	s_movk_i32 s4, 0x121
	s_cselect_b32 s4, s4, 0x120
	s_mul_i32 s4, s3, s4
	s_movk_i32 s0, 0x2c1
	s_cselect_b32 s5, s0, 0x2c0
	s_add_i32 s4, s4, s1
	s_mul_hi_i32 s0, s4, 0x38e38e39
	s_lshr_b32 s6, s0, 31
	s_ashr_i32 s0, s0, 5
	s_add_i32 s0, s0, s6
	s_mul_i32 s6, s0, 0x90
	s_sub_i32 s4, s4, s6
	s_lshl_b32 s7, s0, 3
	s_bfe_u32 s0, s4, 0x3001c
	s_add_i32 s6, s4, s0
	s_sext_i32_i16 s8, s6
	s_and_b32 s6, s6, 0xfff8
	s_sub_i32 s4, s4, s6
	s_sext_i32_i16 s4, s4
	s_add_i32 s10, s7, s4
	s_ashr_i32 s4, s8, 3
	s_add_i32 s2, s2, s1
	v_writelane_b32 v254, s4, 55
	s_ashr_i32 s4, s2, 31
	s_lshr_b32 s4, s4, 26
	s_add_i32 s4, s2, s4
	s_ashr_i32 s6, s4, 6
	s_and_b32 s4, s4, 0xffc0
	s_sub_i32 s4, s2, s4
	s_bfe_i32 s2, s4, 0x80000
	s_bfe_u32 s2, s2, 0x3000c
	s_add_i32 s7, s4, s2
	s_bfe_i32 s2, s7, 0x80000
	s_and_b32 s7, s7, 0xf8
	s_sub_i32 s4, s4, s7
	s_mul_i32 s3, s3, s5
	s_lshr_b32 s0, s8, 3
	s_lshl_b32 s6, s6, 3
	s_sext_i32_i16 s8, s2
	s_sext_i32_i8 s4, s4
	s_add_i32 s3, s3, s1
	s_and_b32 s4, s8, 3
	s_add_i32 s12, s6, s4
	s_lshr_b32 s4, s8, 5
	s_lshl2_add_u32 s12, s4, s12
	s_bfe_u32 s4, s8, 0x30002
	s_lshl_b32 s8, s4, 3
	s_ashr_i32 s4, s8, 3
	s_mul_hi_i32 s1, s3, 0x2e8ba2e9
	v_writelane_b32 v254, s4, 56
	s_lshr_b32 s4, s1, 31
	s_ashr_i32 s1, s1, 6
	s_add_i32 s1, s1, s4
	s_lshl_b32 s5, s1, 3
	s_mulk_i32 s1, 0x160
	s_sub_i32 s1, s3, s1
	s_bfe_u32 s3, s1, 0x3001c
	s_add_i32 s3, s1, s3
	s_sext_i32_i16 s6, s3
	s_and_b32 s3, s3, 0xfff8
	s_sub_i32 s1, s1, s3
	s_sext_i32_i16 s1, s1
	s_add_i32 s14, s5, s1
	s_ashr_i32 s1, s6, 3
	v_writelane_b32 v254, s1, 57
	s_bfe_i64 s[0:1], s[0:1], 0x100000
	s_lshl_b64 s[0:1], s[0:1], 20
	s_lshr_b32 s2, s8, 3
	v_writelane_b32 v254, s0, 58
	s_lshr_b32 s4, s6, 3
	s_mov_b32 s6, s72
	v_writelane_b32 v254, s1, 59
	s_bfe_i64 s[0:1], s[2:3], 0x100000
	s_lshl_b64 s[0:1], s[0:1], 20
	v_writelane_b32 v254, s0, 60
	s_mov_b32 s7, s72
	s_ashr_i32 s11, s10, 31
	v_writelane_b32 v254, s1, 61
	s_bfe_i64 s[0:1], s[4:5], 0x100000
	s_lshl_b64 s[0:1], s[0:1], 20
	v_writelane_b32 v254, s0, 62
	s_mov_b32 s4, 0x3f803f80
	s_mov_b32 s5, s72
	v_writelane_b32 v254, s1, 63
	s_lshl_b32 s0, s9, 11
	v_writelane_b32 v255, s0, 0
	s_lshl_b32 s0, s84, 11
	v_writelane_b32 v255, s0, 1
	s_add_i32 s0, 0, 0x21400
	v_writelane_b32 v255, s0, 2
	s_add_i32 s0, 0, 0x20160
	v_writelane_b32 v255, s0, 3
	s_add_i32 s0, 0, 0x20164
	v_writelane_b32 v255, s0, 4
	s_add_i32 s0, 0, 0x9000
	v_writelane_b32 v255, s0, 5
	s_add_i32 s0, 0, 0x11400
	v_writelane_b32 v255, s0, 6
	v_writelane_b32 v255, s4, 7
	s_add_i32 s0, 0, 0x1d200
	s_ashr_i32 s13, s12, 31
	v_writelane_b32 v255, s5, 8
	v_writelane_b32 v255, s6, 9
	v_writelane_b32 v255, s7, 10
	v_writelane_b32 v255, s0, 11
	s_mov_b32 s0, s10
	v_writelane_b32 v255, s0, 12
	s_ashr_i32 s15, s14, 31
	s_movk_i32 s83, 0x90
	v_writelane_b32 v255, s1, 13
	s_lshl_b64 s[0:1], s[10:11], 20
	v_writelane_b32 v255, s0, 14
	s_movk_i32 s33, 0x2000
	s_movk_i32 s85, 0x4000
	v_writelane_b32 v255, s1, 15
	s_mov_b32 s0, s12
	v_writelane_b32 v255, s0, 16
	s_movk_i32 s56, 0x6000
	s_mov_b32 s63, 0x1a000
	v_writelane_b32 v255, s1, 17
	s_lshl_b64 s[0:1], s[12:13], 20
	v_writelane_b32 v255, s0, 18
	s_mov_b32 s93, 0x1e000
	s_mov_b32 s49, 0xffff0000
	v_writelane_b32 v255, s1, 19
	s_mov_b32 s0, s14
	v_writelane_b32 v255, s0, 20
	v_mov_b32_e32 v219, 0x358637bd
	s_mov_b32 s90, 0x9000
	v_writelane_b32 v255, s1, 21
	s_lshl_b64 s[0:1], s[14:15], 20
	v_writelane_b32 v255, s0, 22
	s_add_i32 s87, 0, 0x1d000
	s_add_i32 s48, 0, 0x1cc00
	v_writelane_b32 v255, s1, 23
	v_writelane_b32 v255, s84, 24
	v_writelane_b32 v255, s59, 25
	v_writelane_b32 v255, s76, 26
	s_mov_b32 s91, 0xb000
	s_mov_b32 s57, 0xd000
	v_writelane_b32 v255, s77, 27
	v_writelane_b32 v255, s75, 28
	v_writelane_b32 v255, s78, 29
	v_writelane_b32 v255, s64, 30
	s_mov_b32 s62, 0xf000
	s_movk_i32 s3, 0x3000
	v_mov_b32_e32 v222, 0x2200
	v_mov_b32_e32 v223, 0xff800000
	v_mov_b32_e32 v224, 0x3fb8aa3b
	v_mov_b32_e32 v246, v1
	v_mov_b32_e32 v247, v1
	v_mov_b32_e32 v248, v1
	v_mov_b32_e32 v249, v1
	v_mov_b64_e32 v[174:175], 0x400
	v_mov_b64_e32 v[176:177], 0x3ff
	s_mov_b64 s[96:97], 0x80
	s_mov_b32 s92, 0x3f317218
	s_mov_b32 s86, 0x3fb8aa3b
	s_mov_b32 s82, 0x3d2df14c
	s_mov_b32 s6, s89
	v_writelane_b32 v255, s65, 31
	s_waitcnt lgkmcnt(0)
	s_barrier
	s_branch .LBB0_261

.LBB0_615:
	s_ashr_i32 s21, s21, 3
	s_add_i32 s21, s26, s21
	s_ashr_i32 s23, s21, 31
	s_lshr_b32 s23, s23, 26
	s_add_i32 s23, s21, s23
	s_ashr_i32 s24, s23, 6
	s_lshl_b32 s25, s24, 3
	s_sub_i32 s24, 0x80, s25
	s_min_i32 s26, s24, 8
	s_abs_i32 s24, s26
	v_cvt_f32_u32_e32 v0, s24
	s_sub_i32 s28, 0, s24
	s_andn2_b32 s23, s23, 63
	s_sub_i32 s21, s21, s23
	v_rcp_iflag_f32_e32 v0, v0
	s_abs_i32 s23, s21
	s_xor_b32 s27, s21, s26
	s_ashr_i32 s27, s27, 31
	v_mul_f32_e32 v0, 0x4f7ffffe, v0
	v_cvt_u32_f32_e32 v0, v0
	s_nop 0
	v_readfirstlane_b32 s29, v0
	s_mul_i32 s28, s28, s29
	s_mul_hi_u32 s28, s29, s28
	s_add_i32 s29, s29, s28
	s_mul_hi_u32 s28, s23, s29
	s_mul_i32 s29, s28, s24
	s_sub_i32 s23, s23, s29
	s_add_i32 s30, s28, 1
	s_sub_i32 s29, s23, s24
	s_cmp_ge_u32 s23, s24
	s_cselect_b32 s28, s30, s28
	s_cselect_b32 s23, s29, s23
	s_add_i32 s29, s28, 1
	s_cmp_ge_u32 s23, s24
	s_cselect_b32 s23, s29, s28
	s_xor_b32 s23, s23, s27
	s_sub_i32 s24, s23, s27
	s_mul_i32 s23, s24, s26
	s_sub_i32 s21, s21, s23
	s_lshl3_add_u32 s23, s24, s21
	s_bfe_u32 s24, s23, 0x30002
	s_and_b32 s21, s23, 3
	s_lshr_b32 s23, s23, 5
	s_lshl2_add_u32 s21, s23, s21
	s_add_i32 s26, s25, s21

.LBB0_899:
	s_ashr_i32 s6, s19, 3
	s_add_i32 s6, s22, s6
	s_ashr_i32 s7, s6, 31
	s_lshr_b32 s7, s7, 26
	s_add_i32 s7, s6, s7
	s_ashr_i32 s19, s7, 6
	s_lshl_b32 s19, s19, 3
	s_sub_i32 s21, 0x80, s19
	s_min_i32 s21, s21, 8
	s_abs_i32 s22, s21
	v_cvt_f32_u32_e32 v0, s22
	s_sub_i32 s24, 0, s22
	s_andn2_b32 s7, s7, 63
	s_sub_i32 s6, s6, s7
	v_rcp_iflag_f32_e32 v0, v0
	s_abs_i32 s7, s6
	s_xor_b32 s23, s6, s21
	s_ashr_i32 s23, s23, 31
	v_mul_f32_e32 v0, 0x4f7ffffe, v0
	v_cvt_u32_f32_e32 v0, v0
	s_nop 0
	v_readfirstlane_b32 s25, v0
	s_mul_i32 s24, s24, s25
	s_mul_hi_u32 s24, s25, s24
	s_add_i32 s25, s25, s24
	s_mul_hi_u32 s24, s7, s25
	s_mul_i32 s25, s24, s22
	s_sub_i32 s7, s7, s25
	s_add_i32 s30, s24, 1
	s_sub_i32 s25, s7, s22
	s_cmp_ge_u32 s7, s22
	s_cselect_b32 s24, s30, s24
	s_cselect_b32 s7, s25, s7
	s_add_i32 s25, s24, 1
	s_cmp_ge_u32 s7, s22
	s_cselect_b32 s7, s25, s24
	s_xor_b32 s7, s7, s23
	s_sub_i32 s56, s7, s23
	s_mul_i32 s7, s56, s21
	s_sub_i32 s6, s6, s7
	s_lshl_b32 s7, s56, 3
	s_add_i32 s7, s7, s6
	s_bfe_u32 s56, s7, 0x30002
	s_and_b32 s6, s7, 3
	s_lshr_b32 s7, s7, 5
	s_lshl2_add_u32 s6, s7, s6
	s_add_i32 s57, s19, s6
